# P8 pass opening: K/V block to LDS images by LDS-DMA (global_load_lds_dwordx4 nt, per-lane source permutation for the swizzled K image and the sub-tiled V image) instead of 16 VGPR loads + 16 ds_write_
# baseline (speedup 1.0000x reference)
.LBB0_967:
	s_cmp_le_i32 s50, s15
	s_mov_b64 s[12:13], -1
	s_cbranch_scc1 .LBB0_964
	s_lshl_b32 s12, s49, 2
	s_add_i32 s20, s12, 0
	s_add_i32 s20, s20, 0x21000
	v_mov_b32_e32 v2, s20
	ds_read_b32 v2, v2
	s_sub_i32 s13, s48, s15
	s_sub_i32 s14, s50, s15
	s_max_i32 s13, s13, 6
	s_max_i32 s14, s14, 6
	s_waitcnt lgkmcnt(0)
	v_readfirstlane_b32 s16, v2
	s_add_i32 s15, s16, 31
	s_ashr_i32 s17, s15, 31
	s_lshr_b32 s17, s17, 27
	s_add_i32 s15, s15, s17
	s_ashr_i32 s18, s15, 5
	s_add_i32 s18, s18, 1
	s_add_i32 s14, s14, -6
	s_add_i32 s17, s90, s13
	s_min_i32 s19, s14, s18
	s_add_i32 s17, s17, -6
	s_mov_b32 s12, 1
	s_cmp_le_i32 s19, s17
	s_mov_b32 s14, 0
	s_cbranch_scc1 .LBB0_963
	s_ashr_i32 s66, s49, 9
	s_and_b32 s21, s49, 63
	s_ashr_i32 s67, s66, 31
	s_bfe_u32 s91, s49, 0x30006
	s_lshl_b32 s14, s21, 18
	s_lshl_b64 s[12:13], s[66:67], 24
	s_or_b32 s12, s12, s14
	s_lshl_b32 s93, s91, 7
	s_or_b32 s12, s12, s93
	s_lshl_b64 s[12:13], s[12:13], 1
	s_add_u32 s14, s78, s12
	v_mov_b32_e32 v73, v0
	s_addc_u32 s15, s79, s13
	s_add_u32 s12, s80, s12
	v_lshlrev_b32_e32 v78, 4, v73
	v_ashrrev_i32_e32 v8, 4, v73
	v_and_b32_e32 v2, 0xf0, v78
	s_addc_u32 s13, s81, s13
	v_ashrrev_i32_e32 v9, 31, v8
	v_lshl_add_u64 v[4:5], s[14:15], 0, v[2:3]
	v_lshl_add_u64 v[6:7], s[12:13], 0, v[2:3]
	v_lshlrev_b64 v[8:9], 11, v[8:9]
	v_lshl_add_u64 v[10:11], v[4:5], 0, v[8:9]
	v_lshl_add_u64 v[8:9], v[6:7], 0, v[8:9]
	v_add_u32_e32 v77, 0x200, v73
	s_barrier
	v_readfirstlane_b32 s98, v73
	s_lshr_b32 s98, s98, 6
	s_lshl_b32 s99, s98, 10
	v_lshrrev_b32_e32 v64, 4, v198
	v_lshl_add_u32 v64, s98, 2, v64
	v_and_b32_e32 v66, 15, v64
	v_and_b32_e32 v67, 15, v198
	v_xor_b32_e32 v66, v66, v67
	v_lshlrev_b32_e32 v66, 4, v66
	v_lshl_add_u32 v64, v64, 11, v66
	v_bfe_u32 v65, v198, 2, 2
	v_bfe_u32 v66, v198, 4, 1
	v_lshl_add_u32 v65, v66, 3, v65
	v_lshlrev_b32_e32 v65, 11, v65
	v_lshrrev_b32_e32 v66, 5, v198
	v_lshl_add_u32 v65, v66, 6, v65
	v_and_b32_e32 v66, 3, v198
	v_lshl_add_u32 v65, v66, 4, v65
	s_bfe_u32 s100, s98, 0x10001
	s_lshl_b32 s100, s100, 2
	s_lshr_b32 s101, s98, 2
	s_lshl_b32 s101, s101, 4
	s_add_i32 s100, s100, s101
	s_lshl_b32 s100, s100, 11
	s_and_b32 s101, s98, 1
	s_lshl_b32 s101, s101, 7
	s_add_i32 s100, s100, s101
	v_add_u32_e32 v65, s100, v65
	s_add_i32 m0, s99, 0x0
	s_add_u32 s100, s14, 0x0
	s_addc_u32 s101, s15, 0
	global_load_lds_dwordx4 v64, s[100:101] nt
	s_add_i32 m0, s99, 0x10000
	s_add_u32 s100, s12, 0x0
	s_addc_u32 s101, s13, 0
	global_load_lds_dwordx4 v65, s[100:101] nt
	s_add_i32 m0, s99, 0x2000
	s_add_u32 s100, s14, 0x10000
	s_addc_u32 s101, s15, 0
	global_load_lds_dwordx4 v64, s[100:101] nt
	s_add_i32 m0, s99, 0x12000
	s_add_u32 s100, s12, 0x10000
	s_addc_u32 s101, s13, 0
	global_load_lds_dwordx4 v65, s[100:101] nt
	s_add_i32 m0, s99, 0x4000
	s_add_u32 s100, s14, 0x20000
	s_addc_u32 s101, s15, 0
	global_load_lds_dwordx4 v64, s[100:101] nt
	s_add_i32 m0, s99, 0x14000
	s_add_u32 s100, s12, 0x20000
	s_addc_u32 s101, s13, 0
	global_load_lds_dwordx4 v65, s[100:101] nt
	s_add_i32 m0, s99, 0x6000
	s_add_u32 s100, s14, 0x30000
	s_addc_u32 s101, s15, 0
	global_load_lds_dwordx4 v64, s[100:101] nt
	s_add_i32 m0, s99, 0x16000
	s_add_u32 s100, s12, 0x30000
	s_addc_u32 s101, s13, 0
	global_load_lds_dwordx4 v65, s[100:101] nt
	s_add_i32 m0, s99, 0x8000
	s_add_u32 s100, s14, 0x40000
	s_addc_u32 s101, s15, 0
	global_load_lds_dwordx4 v64, s[100:101] nt
	s_add_i32 m0, s99, 0x18000
	s_add_u32 s100, s12, 0x40000
	s_addc_u32 s101, s13, 0
	global_load_lds_dwordx4 v65, s[100:101] nt
	s_add_i32 m0, s99, 0xa000
	s_add_u32 s100, s14, 0x50000
	s_addc_u32 s101, s15, 0
	global_load_lds_dwordx4 v64, s[100:101] nt
	s_add_i32 m0, s99, 0x1a000
	s_add_u32 s100, s12, 0x50000
	s_addc_u32 s101, s13, 0
	global_load_lds_dwordx4 v65, s[100:101] nt
	s_add_i32 m0, s99, 0xc000
	s_add_u32 s100, s14, 0x60000
	s_addc_u32 s101, s15, 0
	global_load_lds_dwordx4 v64, s[100:101] nt
	s_add_i32 m0, s99, 0x1c000
	s_add_u32 s100, s12, 0x60000
	s_addc_u32 s101, s13, 0
	global_load_lds_dwordx4 v65, s[100:101] nt
	s_add_i32 m0, s99, 0xe000
	s_add_u32 s100, s14, 0x70000
	s_addc_u32 s101, s15, 0
	global_load_lds_dwordx4 v64, s[100:101] nt
	s_add_i32 m0, s99, 0x1e000
	s_add_u32 s100, s12, 0x70000
	s_addc_u32 s101, s13, 0
	global_load_lds_dwordx4 v65, s[100:101] nt
	v_mov_b32_e32 v2, s83
	ds_read_b32 v2, v2
	s_waitcnt lgkmcnt(0)
	v_cmp_eq_u32_e64 s[12:13], s49, v2
	v_cmp_ne_u32_e32 vcc, s49, v2
	v_xor_b32_e32 v2, s49, v2
	v_cmp_ne_u32_e64 s[14:15], -1, v2
	s_and_b64 s[22:23], vcc, s[14:15]
	s_mov_b64 s[14:15], -1
	s_and_b64 vcc, exec, s[22:23]
	s_cbranch_vccz .LBB0_973
	v_cmp_lt_u32_e32 vcc, s21, v198
	v_mov_b32_e32 v2, 0
	v_mov_b32_e32 v79, 0
	s_and_saveexec_b64 s[14:15], vcc
	s_cbranch_execz .LBB0_972
	s_and_b32 s22, s49, 0xfffffe00
	s_lshl_b32 s23, s91, 6
	s_or_b32 s22, s23, s22
	v_or_b32_e32 v2, s22, v198
	v_mov_b64_e32 v[68:69], s[56:57]
	v_mad_i64_i32 v[68:69], s[22:23], v2, s84, v[68:69]
	s_lshl_b32 s54, s21, 1
	v_lshl_add_u64 v[68:69], v[68:69], 0, s[54:55]
	global_load_dword v2, v[68:69], off
	s_waitcnt vmcnt(0)
	v_and_b32_e32 v79, 0xffff, v2
	v_lshrrev_b32_e32 v2, 16, v2

.LBB0_988:
	s_or_b64 exec, exec, s[12:13]
	v_cmp_eq_u32_e32 vcc, 0, v73
	s_and_saveexec_b64 s[12:13], vcc
	v_mov_b32_e32 v2, s87
	ds_write_b32 v2, v3
	s_or_b64 exec, exec, s[12:13]
	s_andn2_b64 vcc, exec, s[60:61]
	v_cndmask_b32_e64 v221, 0, 1, s[64:65]
	s_mov_b64 s[14:15], s[62:63]
	s_waitcnt vmcnt(0)
	s_waitcnt lgkmcnt(0)
	s_barrier
	s_cbranch_vccnz .LBB0_1015
	v_readfirstlane_b32 s12, v221
	s_add_i32 s95, s49, s12
	s_cmpk_lt_i32 s95, 0x400
	s_mov_b64 s[14:15], -1
	s_cbranch_scc0 .LBB0_1015
	s_and_b32 s15, s95, 63
	s_bfe_u32 s14, s95, 0x30006
	v_cmp_lt_u32_e32 vcc, s15, v198
	v_mov_b32_e32 v6, 0
	v_mov_b32_e32 v2, 0
	s_and_saveexec_b64 s[12:13], vcc
	s_cbranch_execz .LBB0_994
	s_and_b32 s16, s95, 0xfffffe00
	s_lshl_b32 s17, s14, 6
	s_or_b32 s16, s17, s16
	v_or_b32_e32 v2, s16, v198
	v_mov_b64_e32 v[4:5], s[56:57]
	v_mad_i64_i32 v[4:5], s[16:17], v2, s84, v[4:5]
	s_lshl_b32 s54, s15, 1
	v_lshl_add_u64 v[4:5], v[4:5], 0, s[54:55]
	global_load_dword v4, v[4:5], off
	s_waitcnt vmcnt(0)
	v_lshrrev_b32_e32 v2, 16, v4
	v_and_b32_e32 v6, 0xffff, v4

	.amdhsa_kernel _Z13hawk_moba_fwd4Args
		.amdhsa_group_segment_fixed_size 0
		.amdhsa_private_segment_fixed_size 0
		.amdhsa_kernarg_size 424
		.amdhsa_user_sgpr_count 2
		.amdhsa_user_sgpr_dispatch_ptr 0
		.amdhsa_user_sgpr_queue_ptr 0
		.amdhsa_user_sgpr_kernarg_segment_ptr 1
		.amdhsa_user_sgpr_dispatch_id 0
		.amdhsa_user_sgpr_kernarg_preload_length 0
		.amdhsa_user_sgpr_kernarg_preload_offset 0
		.amdhsa_user_sgpr_private_segment_size 0
		.amdhsa_uses_dynamic_stack 0
		.amdhsa_enable_private_segment 0
		.amdhsa_system_sgpr_workgroup_id_x 1
		.amdhsa_system_sgpr_workgroup_id_y 0
		.amdhsa_system_sgpr_workgroup_id_z 0
		.amdhsa_system_sgpr_workgroup_info 0
		.amdhsa_system_vgpr_workitem_id 0
		.amdhsa_next_free_vgpr 256
		.amdhsa_next_free_sgpr 102
		.amdhsa_accum_offset 256
		.amdhsa_reserve_vcc 1
		.amdhsa_float_round_mode_32 0
		.amdhsa_float_round_mode_16_64 0
		.amdhsa_float_denorm_mode_32 3
		.amdhsa_float_denorm_mode_16_64 3
		.amdhsa_dx10_clamp 1
		.amdhsa_ieee_mode 1
		.amdhsa_fp16_overflow 0
		.amdhsa_tg_split 0
		.amdhsa_exception_fp_ieee_invalid_op 0
		.amdhsa_exception_fp_denorm_src 0
		.amdhsa_exception_fp_ieee_div_zero 0
		.amdhsa_exception_fp_ieee_overflow 0
		.amdhsa_exception_fp_ieee_underflow 0
		.amdhsa_exception_fp_ieee_inexact 0
		.amdhsa_exception_int_div_zero 0
	.end_amdhsa_kernel

amdhsa.kernels:
  - .agpr_count:     0
    .args:
      - .offset:         0
        .size:           168
        .value_kind:     by_value
      - .offset:         168
        .size:           4
        .value_kind:     hidden_block_count_x
      - .offset:         172
        .size:           4
        .value_kind:     hidden_block_count_y
      - .offset:         176
        .size:           4
        .value_kind:     hidden_block_count_z
      - .offset:         180
        .size:           2
        .value_kind:     hidden_group_size_x
      - .offset:         182
        .size:           2
        .value_kind:     hidden_group_size_y
      - .offset:         184
        .size:           2
        .value_kind:     hidden_group_size_z
      - .offset:         186
        .size:           2
        .value_kind:     hidden_remainder_x
      - .offset:         188
        .size:           2
        .value_kind:     hidden_remainder_y
      - .offset:         190
        .size:           2
        .value_kind:     hidden_remainder_z
      - .offset:         208
        .size:           8
        .value_kind:     hidden_global_offset_x
      - .offset:         216
        .size:           8
        .value_kind:     hidden_global_offset_y
      - .offset:         224
        .size:           8
        .value_kind:     hidden_global_offset_z
      - .offset:         232
        .size:           2
        .value_kind:     hidden_grid_dims
      - .offset:         288
        .size:           4
        .value_kind:     hidden_dynamic_lds_size
    .group_segment_fixed_size: 0
    .kernarg_segment_align: 8
    .kernarg_segment_size: 424
    .language:       OpenCL C
    .language_version:
      - 2
      - 0
    .max_flat_workgroup_size: 512
    .name:           _Z13hawk_moba_fwd4Args
    .private_segment_fixed_size: 0
    .sgpr_count:     108
    .sgpr_spill_count: 0
    .symbol:         _Z13hawk_moba_fwd4Args.kd
    .uniform_work_group_size: 1
    .uses_dynamic_stack: false
    .vgpr_count:     256
    .vgpr_spill_count: 0
    .wavefront_size: 64
